# v107 plus static s_setprio 1 for waves 0-3 across the P3 owner-computes tail (k-norm, transposes, mLSTM pre-pass), reset to 0 before the P3->P5 sync
# baseline (speedup 1.0000x reference)
.LBB0_137:
	s_cmp_lt_u32 s76, 4
	s_cbranch_scc0 .Lp3prio_done
	s_setprio 1

.LBB0_306:
	s_setprio 0
	s_waitcnt vmcnt(0) lgkmcnt(0)
	s_barrier
	s_and_saveexec_b64 s[4:5], s[88:89]
	s_cbranch_execz .LBB0_316
	buffer_wbl2 sc1
	s_load_dwordx2 s[8:9], s[80:81], -0x8
	s_mul_i32 s10, s33, 3
	v_mov_b32_e32 v2, 0
	v_mov_b32_e32 v3, 1
	s_waitcnt vmcnt(0) lgkmcnt(0)
	global_atomic_add v1, v2, v3, s[8:9] offset:2048 sc0
	s_waitcnt vmcnt(0)
	v_readfirstlane_b32 s11, v1
	s_add_i32 s11, s11, 1
	s_cmp_lg_u32 s11, s10
	s_cbranch_scc1 .Lgb2_poll
	global_atomic_add v2, v3, s[8:9] offset:3072
